# first XCD barrier: the 16 discovery polls issued as one batch; redundant S0 barrier skipped in layer 1
# baseline (speedup 1.0000x reference)
; DI unsigned xb_ld(unsigned* p) { return __hip_atomic_load(p, __ATOMIC_RELAXED, __HIP_MEMORY_SCOPE_AGENT); }
; DI void xcd_barrier_complete(unsigned* bar, unsigned x, unsigned& nloc, unsigned& nx) {
;     ...
;   for (;;) {
;     sum = 0u; cnt = 0u; mine = 0u;
; #pragma unroll
;     for (unsigned j = 0; j < 16; ++j) { const unsigned c = xb_ld(&bar[XB_XCNT(j)]); sum += c; cnt += (c > 0u) ? 1u : 0u; mine = (j == x) ? c : mine; }
;     if (sum == G) break;
;     __builtin_amdgcn_s_sleep(1);
;     if ((++sp & 255u) == 0u) { if (xb_ld(&bar[XB_TMO])) break; if (sp > XB_SPIN_CAP) { atomicAdd(&bar[XB_TMO], 1u); break; } }
;   }
.Lgs_1273:
	v_readlane_b32 s16, v253, 25
	v_readlane_b32 s17, v253, 26
	s_mov_b64 s[36:37], -1
	s_mov_b64 s[38:39], -1
	s_waitcnt lgkmcnt(0)
	s_nop 4
	global_load_dword v0, v173, s[16:17] sc1
	global_load_dword v1, v173, s[16:17] offset:256 sc1
	global_load_dword v2, v173, s[16:17] offset:512 sc1
	global_load_dword v3, v173, s[16:17] offset:768 sc1
	global_load_dword v4, v173, s[16:17] offset:1024 sc1
	global_load_dword v5, v173, s[16:17] offset:1280 sc1
	global_load_dword v6, v173, s[16:17] offset:1536 sc1
	global_load_dword v7, v173, s[16:17] offset:1792 sc1
	global_load_dword v8, v173, s[16:17] offset:2048 sc1
	global_load_dword v9, v173, s[16:17] offset:2304 sc1
	global_load_dword v10, v173, s[16:17] offset:2560 sc1
	global_load_dword v11, v173, s[16:17] offset:2816 sc1
	global_load_dword v12, v173, s[16:17] offset:3072 sc1
	global_load_dword v13, v173, s[16:17] offset:3328 sc1
	global_load_dword v14, v173, s[16:17] offset:3584 sc1
	global_load_dword v15, v173, s[16:17] offset:3840 sc1
	v_readlane_b32 s16, v253, 55
	v_readlane_b32 s17, v253, 56
	s_waitcnt vmcnt(0)
	v_add_u32_e32 v16, v1, v0
	v_add_u32_e32 v16, v16, v2
	v_add_u32_e32 v16, v16, v3
	v_add_u32_e32 v16, v16, v4
	v_add_u32_e32 v16, v16, v5
	v_add_u32_e32 v16, v16, v6
	v_add_u32_e32 v16, v16, v7
	v_add_u32_e32 v16, v16, v8
	v_add_u32_e32 v16, v16, v9
	v_add_u32_e32 v16, v16, v10
	v_add_u32_e32 v16, v16, v11
	v_add_u32_e32 v16, v16, v12
	v_add_u32_e32 v16, v16, v13
	v_add_u32_e32 v16, v16, v14
	v_add_u32_e32 v16, v16, v15
	v_cmp_eq_u32_e32 vcc, s55, v16
	s_cbranch_vccnz .Lgs_1272
	s_and_b32 s36, s42, 0xff
	s_cmp_eq_u32 s36, 0
	s_mov_b64 s[36:37], -1
	s_mov_b64 s[40:41], -1
	s_sleep 1
	s_cbranch_scc1 .Lgs_1277
	s_and_b64 vcc, exec, s[40:41]
	s_cbranch_vccz .Lgs_1272

; DI void xcd_barrier(const XcdBarrier& b) {
;   asm volatile("s_waitcnt vmcnt(0)" ::: "memory");
;   __syncthreads();
;   if (threadIdx.x == 0) {
;     unsigned* bar = b.bar;
;     __builtin_amdgcn_s_waitcnt(0);
;     unsigned nloc = b.st[0], nx = b.st[1];
;     if (nloc == 0u) { xcd_barrier_complete(bar, b.x, nloc, nx); b.st[0] = nloc; b.st[1] = nx; }
.Ln1_done:
.LBB0_362:
	s_or_b64 exec, exec, s[0:1]
	v_readlane_b32 s0, v254, 8
	s_waitcnt vmcnt(0)
	v_readlane_b32 s1, v254, 9
	s_xor_b64 s[62:63], s[0:1], -1
	s_barrier
	s_mov_b64 s[0:1], exec
	v_readlane_b32 s34, v253, 1
	v_readlane_b32 s35, v253, 2
	s_and_b64 s[34:35], s[0:1], s[34:35]
	s_mov_b64 exec, s[34:35]
	s_cmp_lg_u64 s[70:71], 0
	s_cbranch_scc1 .LBB0_414
	s_cbranch_execz .LBB0_414
	v_readlane_b32 s13, v255, 62
	s_waitcnt vmcnt(0) expcnt(0) lgkmcnt(0)
	s_nop 0
	v_mov_b32_e32 v0, s13
	ds_read_b32 v2, v0
	v_readlane_b32 s13, v255, 63
	s_waitcnt lgkmcnt(0)
	v_cmp_ne_u32_e32 vcc, 0, v2
	v_mov_b32_e32 v0, s13
	ds_read_b32 v0, v0
	s_cbranch_vccnz .LBB0_378
	s_mov_b32 s13, 1
	s_branch .LBB0_366
